# residual-stream loads in the three residual GEMM epilogues take the nt hint (read exactly once)
# baseline (speedup 1.0000x reference)
;     __device__ __forceinline__ void operator()(const f32x4 (&acc)[2][2][4][2], const Unit& u, int wr, int wc, int fr, int fq) const {
;     ...
;         const int row0 = u.pm * BM + wr * 64 + fr, col0 = u.pn * BM + wc * 32 + 8 * fq;
;         f32x4 gv[2][2];
; #pragma unroll
;         for (int bj = 0; bj < 2; ++bj)
; #pragma unroll
;             for (int n = 0; n < 2; ++n) gv[bj][n] = An ? *(const f32x4*)(gn + col0 + bj * HALF + 4 * n) : (f32x4){0.f, 0.f, 0.f, 0.f};
;         const float* bb = (u.pm * BM < TP) ? base0 : base1 - (size_t)TP * D;
; #pragma unroll
;         for (int ai = 0; ai < 2; ++ai) {
;             if (quad >= 0 && (quad >> 1) != ai) continue;
;             f32x4 rr[4][2][2];
; #pragma unroll
;             for (int m = 0; m < 4; ++m)
; #pragma unroll
;                 for (int bj = 0; bj < 2; ++bj) { const size_t off = (size_t)(row0 + ai * HALF + m * 16) * D + col0 + bj * HALF;
;                     if (quad >= 0 && (quad & 1) != bj) { rr[m][bj][0] = (f32x4){0.f, 0.f, 0.f, 0.f}; rr[m][bj][1] = rr[m][bj][0]; }
;                     else { rr[m][bj][0] = *(const f32x4*)(bb + off); rr[m][bj][1] = *(const f32x4*)(bb + off + 4); } }
;             __builtin_amdgcn_sched_barrier(0);
; #pragma unroll
;             for (int m = 0; m < 4; ++m) {
;                 const int row = row0 + ai * HALF + m * 16; const size_t off = (size_t)row * D + col0;
;                 float q = 0.f;
; #pragma unroll
;                 for (int bj = 0; bj < 2; ++bj) {
;                     if (quad >= 0 && (quad & 1) != bj) continue;
;                     const f32x4 v0 = rr[m][bj][0] + acc[ai][bj][m][0] * scale, v1 = rr[m][bj][1] + acc[ai][bj][m][1] * scale;
;                     q += dot4(v0) + dot4(v1);
;                     __builtin_nontemporal_store(v0, (f32x4*)(out + off + bj * HALF)); __builtin_nontemporal_store(v1, (f32x4*)(out + off + bj * HALF + 4));
;                     if (An) { const f32x4 a0 = v0 * gv[bj][0], a1 = v1 * gv[bj][1]; u32x4 w; w.x = pk2(a0[0], a0[1]); w.y = pk2(a0[2], a0[3]); w.z = pk2(a1[0], a1[1]); w.w = pk2(a1[2], a1[3]);
;                         *(u32x4*)(An + off + bj * HALF) = w; }
;                 }
;                 q += __shfl_xor(q, 16); q += __shfl_xor(q, 32);
;                 if (fq == 0) __hip_atomic_fetch_add(ss + row, q, __ATOMIC_RELAXED, __HIP_MEMORY_SCOPE_AGENT);
.LBB0_236:
	v_lshl_or_b32 v204, s80, 8, v193
	v_ashrrev_i32_e32 v205, 31, v204
	v_lshl_add_u32 v206, s79, 8, v216
	s_cmp_lt_i32 s79, 64
	v_lshlrev_b64 v[144:145], 2, v[204:205]
	s_cselect_b32 s35, s21, s66
	s_cselect_b32 s34, s20, s57
	v_ashrrev_i32_e32 v207, 31, v206
	v_lshl_add_u64 v[132:133], s[38:39], 0, v[144:145]
	v_lshl_add_u64 v[208:209], s[34:35], 0, v[144:145]
	v_lshlrev_b64 v[144:145], 13, v[206:207]
	v_or_b32_e32 v214, 16, v206
	v_lshl_add_u64 v[144:145], v[208:209], 0, v[144:145]
	v_ashrrev_i32_e32 v215, 31, v214
	global_load_dwordx4 v[136:139], v[132:133], off offset:16 nt
	global_load_dwordx4 v[140:143], v[132:133], off nt
	global_load_dwordx4 v[128:131], v[132:133], off offset:528 nt
	s_nop 0
	global_load_dwordx4 v[132:135], v[132:133], off offset:512 nt
	s_nop 0
	global_load_dwordx4 v[224:227], v[144:145], off offset:16 nt
	global_load_dwordx4 v[228:231], v[144:145], off nt
	global_load_dwordx4 v[232:235], v[144:145], off offset:528 nt
	global_load_dwordx4 v[236:239], v[144:145], off offset:512 nt
	v_lshlrev_b64 v[144:145], 13, v[214:215]
	v_or_b32_e32 v212, 32, v206
	v_lshl_add_u64 v[144:145], v[208:209], 0, v[144:145]
	v_ashrrev_i32_e32 v213, 31, v212
	global_load_dwordx4 v[184:187], v[144:145], off offset:16 nt
	global_load_dwordx4 v[188:191], v[144:145], off nt
	global_load_dwordx4 v[176:179], v[144:145], off offset:528 nt
	global_load_dwordx4 v[180:183], v[144:145], off offset:512 nt
	v_lshlrev_b64 v[144:145], 13, v[212:213]
	v_or_b32_e32 v210, 48, v206
	v_lshl_add_u64 v[144:145], v[208:209], 0, v[144:145]
	v_ashrrev_i32_e32 v211, 31, v210
	global_load_dwordx4 v[168:171], v[144:145], off offset:16 nt
	global_load_dwordx4 v[172:175], v[144:145], off nt
	global_load_dwordx4 v[160:163], v[144:145], off offset:528 nt
	global_load_dwordx4 v[164:167], v[144:145], off offset:512 nt
	v_lshlrev_b64 v[144:145], 13, v[210:211]
	v_lshl_add_u64 v[148:149], v[208:209], 0, v[144:145]
	global_load_dwordx4 v[152:155], v[148:149], off offset:16 nt
	global_load_dwordx4 v[156:159], v[148:149], off nt
	global_load_dwordx4 v[144:147], v[148:149], off offset:528 nt
	s_nop 0
	global_load_dwordx4 v[148:151], v[148:149], off offset:512 nt
	s_waitcnt vmcnt(0)
	v_pk_fma_f32 v[230:231], v[126:127], 0.5, v[230:231] op_sel_hi:[1,0,1]
	v_pk_fma_f32 v[228:229], v[124:125], 0.5, v[228:229] op_sel_hi:[1,0,1]
	v_mul_f32_e32 v223, v231, v231
	v_mul_f32_e32 v219, v229, v229
	v_pk_fma_f32 v[226:227], v[122:123], 0.5, v[226:227] op_sel_hi:[1,0,1]
	v_pk_fma_f32 v[224:225], v[120:121], 0.5, v[224:225] op_sel_hi:[1,0,1]
	v_fmac_f32_e32 v219, v228, v228
	v_fmac_f32_e32 v223, v230, v230
	v_lshlrev_b64 v[220:221], 11, v[206:207]
	v_add_f32_e32 v219, v219, v223
	v_mul_f32_e32 v223, v225, v225
	v_mul_f32_e32 v240, v227, v227
	v_lshl_add_u64 v[220:221], v[220:221], 0, v[204:205]
	v_fmac_f32_e32 v223, v224, v224
	v_fmac_f32_e32 v240, v226, v226
	v_add_f32_e32 v223, v223, v240
	v_lshl_add_u64 v[240:241], v[220:221], 2, s[12:13]
	global_store_dwordx4 v[240:241], v[228:231], off nt
	global_store_dwordx4 v[240:241], v[224:227], off offset:16 nt
	v_pk_mul_f32 v[242:243], v[138:139], v[226:227]
	v_pk_mul_f32 v[230:231], v[142:143], v[230:231]
	v_pk_mul_f32 v[226:227], v[136:137], v[224:225]
	v_pk_mul_f32 v[228:229], v[140:141], v[228:229]
	v_add_f32_e32 v219, v219, v223
	v_cvt_pk_bf16_f32 v224, v228, v229
	v_cvt_pk_bf16_f32 v225, v230, v231
	v_cvt_pk_bf16_f32 v226, v226, v227
	v_cvt_pk_bf16_f32 v227, v242, v243
	v_lshl_add_u64 v[242:243], v[220:221], 1, s[50:51]
	global_store_dwordx4 v[242:243], v[224:227], off
	v_pk_fma_f32 v[230:231], v[90:91], 0.5, v[234:235] op_sel_hi:[1,0,1]
	v_pk_fma_f32 v[228:229], v[88:89], 0.5, v[232:233] op_sel_hi:[1,0,1]
	v_pk_fma_f32 v[226:227], v[94:95], 0.5, v[238:239] op_sel_hi:[1,0,1]
	v_pk_fma_f32 v[224:225], v[92:93], 0.5, v[236:237] op_sel_hi:[1,0,1]
	v_mul_f32_e32 v221, v227, v227
	v_mul_f32_e32 v220, v225, v225
	v_fmac_f32_e32 v220, v224, v224
	v_fmac_f32_e32 v221, v226, v226
	v_add_f32_e32 v220, v220, v221
	v_mul_f32_e32 v221, v229, v229
	v_mul_f32_e32 v223, v231, v231
	v_fmac_f32_e32 v221, v228, v228
	v_fmac_f32_e32 v223, v230, v230
	v_add_f32_e32 v221, v221, v223
	v_add_f32_e32 v220, v220, v221
	v_add_f32_e32 v223, v219, v220
	v_and_b32_e32 v220, 64, v218
	v_xor_b32_e32 v219, 16, v218
	v_add_u32_e32 v232, 64, v220
	v_cmp_lt_i32_e32 vcc, v219, v232
	v_pk_mul_f32 v[220:221], v[132:133], v[224:225]
	global_store_dwordx4 v[240:241], v[224:227], off offset:512 nt
	global_store_dwordx4 v[240:241], v[228:231], off offset:528 nt
	v_cndmask_b32_e32 v219, v218, v219, vcc
	v_lshlrev_b32_e32 v219, 2, v219
	ds_bpermute_b32 v233, v219, v223
	v_cvt_pk_bf16_f32 v224, v220, v221
	v_xor_b32_e32 v220, 32, v218
	v_cmp_lt_i32_e32 vcc, v220, v232
	v_pk_mul_f32 v[226:227], v[134:135], v[226:227]
	s_waitcnt lgkmcnt(0)
	v_add_f32_e32 v221, v223, v233
	v_cndmask_b32_e32 v220, v218, v220, vcc
	v_lshlrev_b32_e32 v220, 2, v220
	ds_bpermute_b32 v223, v220, v221
	v_pk_mul_f32 v[230:231], v[130:131], v[230:231]
	v_pk_mul_f32 v[228:229], v[128:129], v[228:229]
	v_cvt_pk_bf16_f32 v225, v226, v227
	s_nop 0
	v_cvt_pk_bf16_f32 v226, v228, v229
	v_cvt_pk_bf16_f32 v227, v230, v231
	global_store_dwordx4 v[242:243], v[224:227], off offset:256
	s_and_saveexec_b64 s[34:35], s[6:7]
	s_cbranch_execz .LBB0_238
	s_waitcnt lgkmcnt(0)
	v_add_f32_e32 v221, v221, v223
	v_lshl_add_u64 v[224:225], v[206:207], 2, s[52:53]
	global_atomic_add_f32 v[224:225], v221, off

; __device__ __forceinline__ unsigned pk2(float lo, float hi) { unsigned r; asm volatile("v_cvt_pk_bf16_f32 %0, %1, %2" : "=v"(r) : "v"(lo), "v"(hi)); return r; }
; __device__ __forceinline__ float dot4(f32x4 v) { return (v[0] * v[0] + v[1] * v[1]) + (v[2] * v[2] + v[3] * v[3]); }
;     __device__ __forceinline__ void operator()(const f32x4 (&acc)[2][2][4][2], const Unit& u, int wr, int wc, int fr, int fq) const {
;     ...
;             for (int m = 0; m < 4; ++m)
; #pragma unroll
;                 for (int bj = 0; bj < 2; ++bj) { const size_t off = (size_t)(row0 + ai * HALF + m * 16) * D + col0 + bj * HALF;
;                     if (quad >= 0 && (quad & 1) != bj) { rr[m][bj][0] = (f32x4){0.f, 0.f, 0.f, 0.f}; rr[m][bj][1] = rr[m][bj][0]; }
;                     else { rr[m][bj][0] = *(const f32x4*)(bb + off); rr[m][bj][1] = *(const f32x4*)(bb + off + 4); } }
;             __builtin_amdgcn_sched_barrier(0);
; #pragma unroll
;             for (int m = 0; m < 4; ++m) {
;                 const int row = row0 + ai * HALF + m * 16; const size_t off = (size_t)row * D + col0;
;                 float q = 0.f;
; #pragma unroll
;                 for (int bj = 0; bj < 2; ++bj) {
;                     if (quad >= 0 && (quad & 1) != bj) continue;
;                     const f32x4 v0 = rr[m][bj][0] + acc[ai][bj][m][0] * scale, v1 = rr[m][bj][1] + acc[ai][bj][m][1] * scale;
;                     q += dot4(v0) + dot4(v1);
;                     __builtin_nontemporal_store(v0, (f32x4*)(out + off + bj * HALF)); __builtin_nontemporal_store(v1, (f32x4*)(out + off + bj * HALF + 4));
;                     if (An) { const f32x4 a0 = v0 * gv[bj][0], a1 = v1 * gv[bj][1]; u32x4 w; w.x = pk2(a0[0], a0[1]); w.y = pk2(a0[2], a0[3]); w.z = pk2(a1[0], a1[1]); w.w = pk2(a1[2], a1[3]);
;                         *(u32x4*)(An + off + bj * HALF) = w; }
;                 }
;                 q += __shfl_xor(q, 16); q += __shfl_xor(q, 32);
;                 if (fq == 0) __hip_atomic_fetch_add(ss + row, q, __ATOMIC_RELAXED, __HIP_MEMORY_SCOPE_AGENT);
.LBB0_244:
	s_or_b64 exec, exec, s[34:35]
	v_add_u32_e32 v214, 0x80, v206
	v_ashrrev_i32_e32 v215, 31, v214
	s_waitcnt lgkmcnt(0)
	v_lshlrev_b64 v[144:145], 13, v[214:215]
	v_add_u32_e32 v212, 0x90, v206
	v_lshl_add_u64 v[144:145], v[208:209], 0, v[144:145]
	v_ashrrev_i32_e32 v213, 31, v212
	global_load_dwordx4 v[224:227], v[144:145], off offset:16 nt
	global_load_dwordx4 v[228:231], v[144:145], off nt
	global_load_dwordx4 v[232:235], v[144:145], off offset:528 nt
	global_load_dwordx4 v[236:239], v[144:145], off offset:512 nt
	v_lshlrev_b64 v[144:145], 13, v[212:213]
	v_add_u32_e32 v210, 0xa0, v206
	v_lshl_add_u64 v[144:145], v[208:209], 0, v[144:145]
	v_ashrrev_i32_e32 v211, 31, v210
	global_load_dwordx4 v[184:187], v[144:145], off offset:16 nt
	global_load_dwordx4 v[188:191], v[144:145], off nt
	global_load_dwordx4 v[176:179], v[144:145], off offset:528 nt
	global_load_dwordx4 v[180:183], v[144:145], off offset:512 nt
	v_lshlrev_b64 v[144:145], 13, v[210:211]
	v_add_u32_e32 v206, 0xb0, v206
	v_lshl_add_u64 v[144:145], v[208:209], 0, v[144:145]
	v_ashrrev_i32_e32 v207, 31, v206
	global_load_dwordx4 v[168:171], v[144:145], off offset:16 nt
	global_load_dwordx4 v[172:175], v[144:145], off nt
	global_load_dwordx4 v[160:163], v[144:145], off offset:528 nt
	global_load_dwordx4 v[164:167], v[144:145], off offset:512 nt
	v_lshlrev_b64 v[144:145], 13, v[206:207]
	v_lshl_add_u64 v[148:149], v[208:209], 0, v[144:145]
	global_load_dwordx4 v[152:155], v[148:149], off offset:16 nt
	global_load_dwordx4 v[156:159], v[148:149], off nt
	global_load_dwordx4 v[144:147], v[148:149], off offset:528 nt
	s_nop 0
	global_load_dwordx4 v[148:151], v[148:149], off offset:512 nt
	s_waitcnt vmcnt(14)
	v_pk_fma_f32 v[230:231], v[62:63], 0.5, v[230:231] op_sel_hi:[1,0,1]
	v_pk_fma_f32 v[228:229], v[60:61], 0.5, v[228:229] op_sel_hi:[1,0,1]
	v_mul_f32_e32 v223, v231, v231
	v_mul_f32_e32 v221, v229, v229
	v_pk_fma_f32 v[226:227], v[58:59], 0.5, v[226:227] op_sel_hi:[1,0,1]
	v_pk_fma_f32 v[224:225], v[56:57], 0.5, v[224:225] op_sel_hi:[1,0,1]
	v_fmac_f32_e32 v221, v228, v228
	v_fmac_f32_e32 v223, v230, v230
	v_lshlrev_b64 v[208:209], 11, v[214:215]
	v_add_f32_e32 v221, v221, v223
	v_mul_f32_e32 v223, v225, v225
	v_mul_f32_e32 v240, v227, v227
	v_lshl_add_u64 v[208:209], v[208:209], 0, v[204:205]
	v_fmac_f32_e32 v223, v224, v224
	v_fmac_f32_e32 v240, v226, v226
	v_add_f32_e32 v223, v223, v240
	v_lshl_add_u64 v[240:241], v[208:209], 2, s[12:13]
	global_store_dwordx4 v[240:241], v[228:231], off nt
	global_store_dwordx4 v[240:241], v[224:227], off offset:16 nt
	v_pk_mul_f32 v[242:243], v[138:139], v[226:227]
	v_pk_mul_f32 v[230:231], v[142:143], v[230:231]
	v_pk_mul_f32 v[226:227], v[136:137], v[224:225]
	v_pk_mul_f32 v[228:229], v[140:141], v[228:229]
	v_add_f32_e32 v221, v221, v223
	v_cvt_pk_bf16_f32 v224, v228, v229
	v_cvt_pk_bf16_f32 v225, v230, v231
	v_cvt_pk_bf16_f32 v226, v226, v227
	v_cvt_pk_bf16_f32 v227, v242, v243
	v_lshl_add_u64 v[242:243], v[208:209], 1, s[50:51]
	global_store_dwordx4 v[242:243], v[224:227], off
	s_waitcnt vmcnt(16)
	v_pk_fma_f32 v[230:231], v[26:27], 0.5, v[234:235] op_sel_hi:[1,0,1]
	v_pk_fma_f32 v[228:229], v[24:25], 0.5, v[232:233] op_sel_hi:[1,0,1]
	s_waitcnt vmcnt(15)
	v_pk_fma_f32 v[226:227], v[30:31], 0.5, v[238:239] op_sel_hi:[1,0,1]
	v_pk_fma_f32 v[224:225], v[28:29], 0.5, v[236:237] op_sel_hi:[1,0,1]
	v_mul_f32_e32 v209, v227, v227
	v_mul_f32_e32 v208, v225, v225
	v_fmac_f32_e32 v208, v224, v224
	v_fmac_f32_e32 v209, v226, v226
	v_add_f32_e32 v208, v208, v209
	v_mul_f32_e32 v209, v229, v229
	v_mul_f32_e32 v223, v231, v231
	v_fmac_f32_e32 v209, v228, v228
	v_fmac_f32_e32 v223, v230, v230
	v_add_f32_e32 v209, v209, v223
	v_add_f32_e32 v208, v208, v209
	v_add_f32_e32 v221, v221, v208
	ds_bpermute_b32 v223, v219, v221
	v_pk_mul_f32 v[208:209], v[132:133], v[224:225]
	global_store_dwordx4 v[240:241], v[224:227], off offset:512 nt
	global_store_dwordx4 v[240:241], v[228:231], off offset:528 nt
	s_nop 0
	v_cvt_pk_bf16_f32 v224, v208, v209
	s_waitcnt lgkmcnt(0)
	v_add_f32_e32 v208, v221, v223
	ds_bpermute_b32 v209, v220, v208
	v_pk_mul_f32 v[226:227], v[134:135], v[226:227]
	v_pk_mul_f32 v[230:231], v[130:131], v[230:231]
	v_pk_mul_f32 v[228:229], v[128:129], v[228:229]
	v_cvt_pk_bf16_f32 v225, v226, v227
	s_nop 0
	v_cvt_pk_bf16_f32 v226, v228, v229
	v_cvt_pk_bf16_f32 v227, v230, v231
	global_store_dwordx4 v[242:243], v[224:227], off offset:256
	s_and_saveexec_b64 s[34:35], s[6:7]
	s_cbranch_execz .LBB0_246
	s_waitcnt lgkmcnt(0)
	v_add_f32_e32 v221, v208, v209
	v_lshl_add_u64 v[208:209], v[214:215], 2, s[52:53]
	global_atomic_add_f32 v[208:209], v221, off

;     __device__ __forceinline__ void operator()(const f32x4 (&acc)[2][2][4][2], const Unit& u, int wr, int wc, int fr, int fq) const {
;     ...
;         const int row0 = u.pm * BM + wr * 64 + fr, col0 = u.pn * BM + wc * 32 + 8 * fq;
;         f32x4 gv[2][2];
; #pragma unroll
;         for (int bj = 0; bj < 2; ++bj)
; #pragma unroll
;             for (int n = 0; n < 2; ++n) gv[bj][n] = An ? *(const f32x4*)(gn + col0 + bj * HALF + 4 * n) : (f32x4){0.f, 0.f, 0.f, 0.f};
;         const float* bb = (u.pm * BM < TP) ? base0 : base1 - (size_t)TP * D;
; #pragma unroll
;         for (int ai = 0; ai < 2; ++ai) {
;             if (quad >= 0 && (quad >> 1) != ai) continue;
;             f32x4 rr[4][2][2];
; #pragma unroll
;             for (int m = 0; m < 4; ++m)
; #pragma unroll
;                 for (int bj = 0; bj < 2; ++bj) { const size_t off = (size_t)(row0 + ai * HALF + m * 16) * D + col0 + bj * HALF;
;                     if (quad >= 0 && (quad & 1) != bj) { rr[m][bj][0] = (f32x4){0.f, 0.f, 0.f, 0.f}; rr[m][bj][1] = rr[m][bj][0]; }
;                     else { rr[m][bj][0] = *(const f32x4*)(bb + off); rr[m][bj][1] = *(const f32x4*)(bb + off + 4); } }
;             __builtin_amdgcn_sched_barrier(0);
; #pragma unroll
;             for (int m = 0; m < 4; ++m) {
;                 const int row = row0 + ai * HALF + m * 16; const size_t off = (size_t)row * D + col0;
;                 float q = 0.f;
; #pragma unroll
;                 for (int bj = 0; bj < 2; ++bj) {
;                     if (quad >= 0 && (quad & 1) != bj) continue;
;                     const f32x4 v0 = rr[m][bj][0] + acc[ai][bj][m][0] * scale, v1 = rr[m][bj][1] + acc[ai][bj][m][1] * scale;
;                     q += dot4(v0) + dot4(v1);
;                     __builtin_nontemporal_store(v0, (f32x4*)(out + off + bj * HALF)); __builtin_nontemporal_store(v1, (f32x4*)(out + off + bj * HALF + 4));
;                     if (An) { const f32x4 a0 = v0 * gv[bj][0], a1 = v1 * gv[bj][1]; u32x4 w; w.x = pk2(a0[0], a0[1]); w.y = pk2(a0[2], a0[3]); w.z = pk2(a1[0], a1[1]); w.w = pk2(a1[2], a1[3]);
;                         *(u32x4*)(An + off + bj * HALF) = w; }
;                 }
;                 q += __shfl_xor(q, 16); q += __shfl_xor(q, 32);
;                 if (fq == 0) __hip_atomic_fetch_add(ss + row, q, __ATOMIC_RELAXED, __HIP_MEMORY_SCOPE_AGENT);
.LBB0_986:
	v_lshl_or_b32 v204, s77, 8, v193
	v_ashrrev_i32_e32 v205, 31, v204
	v_lshl_add_u32 v208, s58, 8, v223
	v_lshlrev_b64 v[144:145], 2, v[204:205]
	v_ashrrev_i32_e32 v209, 31, v208
	v_or_b32_e32 v218, 16, v208
	v_lshl_add_u64 v[132:133], s[22:23], 0, v[144:145]
	v_lshl_add_u64 v[206:207], s[12:13], 0, v[144:145]
	v_lshlrev_b64 v[144:145], 13, v[208:209]
	v_ashrrev_i32_e32 v219, 31, v218
	v_or_b32_e32 v214, 32, v208
	v_lshl_add_u64 v[242:243], v[206:207], 0, v[144:145]
	v_lshlrev_b64 v[144:145], 13, v[218:219]
	v_ashrrev_i32_e32 v215, 31, v214
	v_or_b32_e32 v210, 48, v208
	v_lshl_add_u64 v[220:221], v[206:207], 0, v[144:145]
	v_lshlrev_b64 v[144:145], 13, v[214:215]
	v_ashrrev_i32_e32 v211, 31, v210
	v_lshl_add_u64 v[216:217], v[206:207], 0, v[144:145]
	v_lshlrev_b64 v[144:145], 13, v[210:211]
	v_lshl_add_u64 v[212:213], v[206:207], 0, v[144:145]
	global_load_dwordx4 v[136:139], v[132:133], off offset:16 nt
	global_load_dwordx4 v[140:143], v[132:133], off nt
	global_load_dwordx4 v[128:131], v[132:133], off offset:528 nt
	s_nop 0
	global_load_dwordx4 v[132:135], v[132:133], off offset:512 nt
	s_nop 0
	global_load_dwordx4 v[226:229], v[242:243], off offset:16 nt
	global_load_dwordx4 v[230:233], v[242:243], off nt
	global_load_dwordx4 v[234:237], v[242:243], off offset:528 nt
	global_load_dwordx4 v[238:241], v[242:243], off offset:512 nt
	global_load_dwordx4 v[184:187], v[220:221], off offset:16 nt
	global_load_dwordx4 v[188:191], v[220:221], off nt
	global_load_dwordx4 v[176:179], v[220:221], off offset:528 nt
	global_load_dwordx4 v[180:183], v[220:221], off offset:512 nt
	global_load_dwordx4 v[168:171], v[216:217], off offset:16 nt
	global_load_dwordx4 v[172:175], v[216:217], off nt
	global_load_dwordx4 v[160:163], v[216:217], off offset:528 nt
	global_load_dwordx4 v[164:167], v[216:217], off offset:512 nt
	global_load_dwordx4 v[152:155], v[212:213], off offset:16 nt
	global_load_dwordx4 v[156:159], v[212:213], off nt
	global_load_dwordx4 v[144:147], v[212:213], off offset:528 nt
	global_load_dwordx4 v[148:151], v[212:213], off offset:512 nt
	s_waitcnt vmcnt(0)
	v_pk_add_f32 v[232:233], v[232:233], v[126:127]
	v_pk_add_f32 v[230:231], v[230:231], v[124:125]
	v_mul_f32_e32 v247, v233, v233
	v_mul_f32_e32 v246, v231, v231
	v_pk_add_f32 v[228:229], v[228:229], v[122:123]
	v_pk_add_f32 v[226:227], v[226:227], v[120:121]
	v_fmac_f32_e32 v246, v230, v230
	v_fmac_f32_e32 v247, v232, v232
	v_add_f32_e32 v246, v246, v247
	v_mul_f32_e32 v247, v227, v227
	v_mul_f32_e32 v248, v229, v229
	v_fmac_f32_e32 v247, v226, v226
	v_fmac_f32_e32 v248, v228, v228
	v_lshlrev_b64 v[244:245], 11, v[208:209]
	v_add_f32_e32 v247, v247, v248
	v_lshl_add_u64 v[244:245], v[244:245], 0, v[204:205]
	v_add_f32_e32 v248, v246, v247
	global_store_dwordx4 v[242:243], v[230:233], off nt
	global_store_dwordx4 v[242:243], v[226:229], off offset:16 nt
	v_pk_mul_f32 v[246:247], v[138:139], v[228:229]
	v_pk_mul_f32 v[232:233], v[142:143], v[232:233]
	v_pk_mul_f32 v[228:229], v[136:137], v[226:227]
	v_pk_mul_f32 v[230:231], v[140:141], v[230:231]
	v_lshl_add_u64 v[244:245], v[244:245], 1, s[46:47]
	v_cvt_pk_bf16_f32 v226, v230, v231
	v_cvt_pk_bf16_f32 v227, v232, v233
	v_cvt_pk_bf16_f32 v228, v228, v229
	v_cvt_pk_bf16_f32 v229, v246, v247
	global_store_dwordx4 v[244:245], v[226:229], off
	v_pk_add_f32 v[230:231], v[240:241], v[94:95]
	v_pk_add_f32 v[236:237], v[236:237], v[90:91]
	v_pk_add_f32 v[228:229], v[238:239], v[92:93]
	v_mul_f32_e32 v227, v231, v231
	v_mul_f32_e32 v226, v229, v229
	v_pk_add_f32 v[234:235], v[234:235], v[88:89]
	v_fmac_f32_e32 v226, v228, v228
	v_fmac_f32_e32 v227, v230, v230
	v_add_f32_e32 v226, v226, v227
	v_mul_f32_e32 v227, v235, v235
	v_mul_f32_e32 v232, v237, v237
	v_fmac_f32_e32 v227, v234, v234
	v_fmac_f32_e32 v232, v236, v236
	v_add_f32_e32 v227, v227, v232
	v_add_f32_e32 v226, v226, v227
	global_store_dwordx4 v[242:243], v[228:231], off offset:512 nt
	global_store_dwordx4 v[242:243], v[234:237], off offset:528 nt
	v_pk_mul_f32 v[232:233], v[134:135], v[230:231]
	v_and_b32_e32 v230, 64, v225
	v_add_f32_e32 v227, v248, v226
	v_xor_b32_e32 v226, 16, v225
	v_add_u32_e32 v231, 64, v230
	v_cmp_lt_i32_e32 vcc, v226, v231
	v_pk_mul_f32 v[228:229], v[132:133], v[228:229]
	v_pk_mul_f32 v[236:237], v[130:131], v[236:237]
	v_cndmask_b32_e32 v226, v225, v226, vcc
	v_lshlrev_b32_e32 v226, 2, v226
	ds_bpermute_b32 v238, v226, v227
	v_cvt_pk_bf16_f32 v230, v228, v229
	v_pk_mul_f32 v[234:235], v[128:129], v[234:235]
	s_waitcnt lgkmcnt(0)
	v_add_f32_e32 v228, v227, v238
	v_xor_b32_e32 v227, 32, v225
	v_cmp_lt_i32_e32 vcc, v227, v231
	v_cvt_pk_bf16_f32 v231, v232, v233
	v_cvt_pk_bf16_f32 v232, v234, v235
	v_cvt_pk_bf16_f32 v233, v236, v237
	global_store_dwordx4 v[244:245], v[230:233], off offset:256
	s_nop 0
	v_cndmask_b32_e32 v227, v225, v227, vcc
	v_lshlrev_b32_e32 v227, 2, v227
	ds_bpermute_b32 v229, v227, v228
	s_and_saveexec_b64 s[34:35], s[8:9]
	s_cbranch_execz .LBB0_988
	s_waitcnt lgkmcnt(0)
	v_add_f32_e32 v230, v228, v229
	v_lshl_add_u64 v[228:229], v[208:209], 2, s[48:49]
	global_atomic_add_f32 v[228:229], v230, off

; __device__ __forceinline__ unsigned pk2(float lo, float hi) { unsigned r; asm volatile("v_cvt_pk_bf16_f32 %0, %1, %2" : "=v"(r) : "v"(lo), "v"(hi)); return r; }
; __device__ __forceinline__ float dot4(f32x4 v) { return (v[0] * v[0] + v[1] * v[1]) + (v[2] * v[2] + v[3] * v[3]); }
;     __device__ __forceinline__ void operator()(const f32x4 (&acc)[2][2][4][2], const Unit& u, int wr, int wc, int fr, int fq) const {
;     ...
;             for (int m = 0; m < 4; ++m)
; #pragma unroll
;                 for (int bj = 0; bj < 2; ++bj) { const size_t off = (size_t)(row0 + ai * HALF + m * 16) * D + col0 + bj * HALF;
;                     if (quad >= 0 && (quad & 1) != bj) { rr[m][bj][0] = (f32x4){0.f, 0.f, 0.f, 0.f}; rr[m][bj][1] = rr[m][bj][0]; }
;                     else { rr[m][bj][0] = *(const f32x4*)(bb + off); rr[m][bj][1] = *(const f32x4*)(bb + off + 4); } }
;             __builtin_amdgcn_sched_barrier(0);
; #pragma unroll
;             for (int m = 0; m < 4; ++m) {
;                 const int row = row0 + ai * HALF + m * 16; const size_t off = (size_t)row * D + col0;
;                 float q = 0.f;
; #pragma unroll
;                 for (int bj = 0; bj < 2; ++bj) {
;                     if (quad >= 0 && (quad & 1) != bj) continue;
;                     const f32x4 v0 = rr[m][bj][0] + acc[ai][bj][m][0] * scale, v1 = rr[m][bj][1] + acc[ai][bj][m][1] * scale;
;                     q += dot4(v0) + dot4(v1);
;                     __builtin_nontemporal_store(v0, (f32x4*)(out + off + bj * HALF)); __builtin_nontemporal_store(v1, (f32x4*)(out + off + bj * HALF + 4));
;                     if (An) { const f32x4 a0 = v0 * gv[bj][0], a1 = v1 * gv[bj][1]; u32x4 w; w.x = pk2(a0[0], a0[1]); w.y = pk2(a0[2], a0[3]); w.z = pk2(a1[0], a1[1]); w.w = pk2(a1[2], a1[3]);
;                         *(u32x4*)(An + off + bj * HALF) = w; }
;                 }
;                 q += __shfl_xor(q, 16); q += __shfl_xor(q, 32);
;                 if (fq == 0) __hip_atomic_fetch_add(ss + row, q, __ATOMIC_RELAXED, __HIP_MEMORY_SCOPE_AGENT);
.LBB0_994:
	s_or_b64 exec, exec, s[34:35]
	v_add_u32_e32 v218, 0x80, v208
	v_ashrrev_i32_e32 v219, 31, v218
	v_add_u32_e32 v214, 0x90, v208
	s_waitcnt lgkmcnt(0)
	v_lshlrev_b64 v[144:145], 13, v[218:219]
	v_ashrrev_i32_e32 v215, 31, v214
	v_add_u32_e32 v210, 0xa0, v208
	v_lshl_add_u64 v[220:221], v[206:207], 0, v[144:145]
	v_lshlrev_b64 v[144:145], 13, v[214:215]
	v_ashrrev_i32_e32 v211, 31, v210
	v_add_u32_e32 v208, 0xb0, v208
	v_lshl_add_u64 v[216:217], v[206:207], 0, v[144:145]
	v_lshlrev_b64 v[144:145], 13, v[210:211]
	v_ashrrev_i32_e32 v209, 31, v208
	v_lshl_add_u64 v[212:213], v[206:207], 0, v[144:145]
	v_lshlrev_b64 v[144:145], 13, v[208:209]
	v_lshl_add_u64 v[206:207], v[206:207], 0, v[144:145]
	global_load_dwordx4 v[228:231], v[220:221], off offset:16 nt
	global_load_dwordx4 v[232:235], v[220:221], off nt
	global_load_dwordx4 v[236:239], v[220:221], off offset:528 nt
	global_load_dwordx4 v[240:243], v[220:221], off offset:512 nt
	global_load_dwordx4 v[184:187], v[216:217], off offset:16 nt
	global_load_dwordx4 v[188:191], v[216:217], off nt
	global_load_dwordx4 v[176:179], v[216:217], off offset:528 nt
	global_load_dwordx4 v[180:183], v[216:217], off offset:512 nt
	global_load_dwordx4 v[168:171], v[212:213], off offset:16 nt
	global_load_dwordx4 v[172:175], v[212:213], off nt
	global_load_dwordx4 v[160:163], v[212:213], off offset:528 nt
	global_load_dwordx4 v[164:167], v[212:213], off offset:512 nt
	global_load_dwordx4 v[152:155], v[206:207], off offset:16 nt
	global_load_dwordx4 v[156:159], v[206:207], off nt
	global_load_dwordx4 v[144:147], v[206:207], off offset:528 nt
	global_load_dwordx4 v[148:151], v[206:207], off offset:512 nt
	s_waitcnt vmcnt(14)
	v_pk_add_f32 v[234:235], v[62:63], v[234:235]
	v_pk_add_f32 v[232:233], v[60:61], v[232:233]
	v_mul_f32_e32 v247, v235, v235
	v_mul_f32_e32 v246, v233, v233
	v_pk_add_f32 v[230:231], v[58:59], v[230:231]
	v_pk_add_f32 v[228:229], v[56:57], v[228:229]
	v_fmac_f32_e32 v246, v232, v232
	v_fmac_f32_e32 v247, v234, v234
	v_add_f32_e32 v246, v246, v247
	v_mul_f32_e32 v247, v229, v229
	v_mul_f32_e32 v248, v231, v231
	v_fmac_f32_e32 v247, v228, v228
	v_fmac_f32_e32 v248, v230, v230
	v_lshlrev_b64 v[244:245], 11, v[218:219]
	v_add_f32_e32 v247, v247, v248
	v_lshl_add_u64 v[244:245], v[244:245], 0, v[204:205]
	v_add_f32_e32 v248, v246, v247
	global_store_dwordx4 v[220:221], v[232:235], off nt
	global_store_dwordx4 v[220:221], v[228:231], off offset:16 nt
	v_pk_mul_f32 v[246:247], v[138:139], v[230:231]
	v_pk_mul_f32 v[234:235], v[142:143], v[234:235]
	v_pk_mul_f32 v[230:231], v[136:137], v[228:229]
	v_pk_mul_f32 v[232:233], v[140:141], v[232:233]
	v_lshl_add_u64 v[244:245], v[244:245], 1, s[46:47]
	v_cvt_pk_bf16_f32 v228, v232, v233
	v_cvt_pk_bf16_f32 v229, v234, v235
	v_cvt_pk_bf16_f32 v230, v230, v231
	v_cvt_pk_bf16_f32 v231, v246, v247
	global_store_dwordx4 v[244:245], v[228:231], off
	s_waitcnt vmcnt(16)
	v_pk_add_f32 v[232:233], v[24:25], v[236:237]
	v_pk_add_f32 v[234:235], v[26:27], v[238:239]
	s_waitcnt vmcnt(15)
	v_pk_add_f32 v[230:231], v[30:31], v[242:243]
	v_pk_add_f32 v[228:229], v[28:29], v[240:241]
	v_mul_f32_e32 v237, v231, v231
	v_mul_f32_e32 v236, v229, v229
	v_fmac_f32_e32 v236, v228, v228
	v_fmac_f32_e32 v237, v230, v230
	v_add_f32_e32 v236, v236, v237
	v_mul_f32_e32 v237, v233, v233
	v_mul_f32_e32 v238, v235, v235
	v_fmac_f32_e32 v237, v232, v232
	v_fmac_f32_e32 v238, v234, v234
	v_add_f32_e32 v237, v237, v238
	v_add_f32_e32 v236, v236, v237
	v_add_f32_e32 v236, v248, v236
	ds_bpermute_b32 v237, v226, v236
	global_store_dwordx4 v[220:221], v[228:231], off offset:512 nt
	global_store_dwordx4 v[220:221], v[232:235], off offset:528 nt
	v_pk_mul_f32 v[220:221], v[132:133], v[228:229]
	v_pk_mul_f32 v[230:231], v[134:135], v[230:231]
	v_cvt_pk_bf16_f32 v228, v220, v221
	s_waitcnt lgkmcnt(0)
	v_add_f32_e32 v220, v236, v237
	ds_bpermute_b32 v221, v227, v220
	v_pk_mul_f32 v[234:235], v[130:131], v[234:235]
	v_pk_mul_f32 v[232:233], v[128:129], v[232:233]
	v_cvt_pk_bf16_f32 v229, v230, v231
	s_nop 0
	v_cvt_pk_bf16_f32 v230, v232, v233
	v_cvt_pk_bf16_f32 v231, v234, v235
	global_store_dwordx4 v[244:245], v[228:231], off offset:256
	s_and_saveexec_b64 s[34:35], s[8:9]
	s_cbranch_execz .LBB0_996
	s_waitcnt lgkmcnt(0)
	v_add_f32_e32 v220, v220, v221
	v_lshl_add_u64 v[218:219], v[218:219], 2, s[48:49]
	global_atomic_add_f32 v[218:219], v220, off

; __device__ __forceinline__ unsigned pk2(float lo, float hi) { unsigned r; asm volatile("v_cvt_pk_bf16_f32 %0, %1, %2" : "=v"(r) : "v"(lo), "v"(hi)); return r; }
; __device__ __forceinline__ float dot4(f32x4 v) { return (v[0] * v[0] + v[1] * v[1]) + (v[2] * v[2] + v[3] * v[3]); }
;     __device__ __forceinline__ void operator()(const f32x4 (&acc)[2][2][4][2], const Unit& u, int wr, int wc, int fr, int fq) const {
;     ...
;             for (int m = 0; m < 4; ++m)
; #pragma unroll
;                 for (int bj = 0; bj < 2; ++bj) { const size_t off = (size_t)(row0 + ai * HALF + m * 16) * D + col0 + bj * HALF;
;                     if (quad >= 0 && (quad & 1) != bj) { rr[m][bj][0] = (f32x4){0.f, 0.f, 0.f, 0.f}; rr[m][bj][1] = rr[m][bj][0]; }
;                     else { rr[m][bj][0] = *(const f32x4*)(bb + off); rr[m][bj][1] = *(const f32x4*)(bb + off + 4); } }
;             __builtin_amdgcn_sched_barrier(0);
; #pragma unroll
;             for (int m = 0; m < 4; ++m) {
;                 const int row = row0 + ai * HALF + m * 16; const size_t off = (size_t)row * D + col0;
;                 float q = 0.f;
; #pragma unroll
;                 for (int bj = 0; bj < 2; ++bj) {
;                     if (quad >= 0 && (quad & 1) != bj) continue;
;                     const f32x4 v0 = rr[m][bj][0] + acc[ai][bj][m][0] * scale, v1 = rr[m][bj][1] + acc[ai][bj][m][1] * scale;
;                     q += dot4(v0) + dot4(v1);
;                     __builtin_nontemporal_store(v0, (f32x4*)(out + off + bj * HALF)); __builtin_nontemporal_store(v1, (f32x4*)(out + off + bj * HALF + 4));
;                     if (An) { const f32x4 a0 = v0 * gv[bj][0], a1 = v1 * gv[bj][1]; u32x4 w; w.x = pk2(a0[0], a0[1]); w.y = pk2(a0[2], a0[3]); w.z = pk2(a1[0], a1[1]); w.w = pk2(a1[2], a1[3]);
;                         *(u32x4*)(An + off + bj * HALF) = w; }
;                 }
;                 q += __shfl_xor(q, 16); q += __shfl_xor(q, 32);
;                 if (fq == 0) __hip_atomic_fetch_add(ss + row, q, __ATOMIC_RELAXED, __HIP_MEMORY_SCOPE_AGENT);
.LBB0_1293:
	v_lshl_or_b32 v188, s82, 8, v177
	v_ashrrev_i32_e32 v189, 31, v188
	v_lshl_add_u32 v192, s81, 8, v206
	v_lshlrev_b64 v[232:233], 2, v[188:189]
	v_ashrrev_i32_e32 v193, 31, v192
	v_or_b32_e32 v202, 16, v192
	v_lshl_add_u64 v[190:191], s[12:13], 0, v[232:233]
	v_lshlrev_b64 v[234:235], 13, v[192:193]
	v_ashrrev_i32_e32 v203, 31, v202
	v_or_b32_e32 v198, 32, v192
	v_or_b32_e32 v194, 48, v192
	v_lshl_add_u64 v[128:129], v[190:191], 0, v[234:235]
	v_lshlrev_b64 v[204:205], 13, v[202:203]
	v_ashrrev_i32_e32 v199, 31, v198
	v_ashrrev_i32_e32 v195, 31, v194
	global_load_dwordx4 v[210:213], v[128:129], off offset:16 nt
	global_load_dwordx4 v[214:217], v[128:129], off nt
	global_load_dwordx4 v[218:221], v[128:129], off offset:528 nt
	global_load_dwordx4 v[224:227], v[128:129], off offset:512 nt
	v_lshl_add_u64 v[128:129], v[190:191], 0, v[204:205]
	v_lshlrev_b64 v[200:201], 13, v[198:199]
	v_lshlrev_b64 v[196:197], 13, v[194:195]
	global_load_dwordx4 v[168:171], v[128:129], off offset:16 nt
	global_load_dwordx4 v[172:175], v[128:129], off nt
	global_load_dwordx4 v[160:163], v[128:129], off offset:528 nt
	global_load_dwordx4 v[164:167], v[128:129], off offset:512 nt
	v_lshl_add_u64 v[128:129], v[190:191], 0, v[200:201]
	v_lshl_add_u64 v[132:133], v[190:191], 0, v[196:197]
	global_load_dwordx4 v[152:155], v[128:129], off offset:16 nt
	global_load_dwordx4 v[156:159], v[128:129], off nt
	global_load_dwordx4 v[144:147], v[128:129], off offset:528 nt
	global_load_dwordx4 v[148:151], v[128:129], off offset:512 nt
	global_load_dwordx4 v[136:139], v[132:133], off offset:16 nt
	global_load_dwordx4 v[140:143], v[132:133], off nt
	s_nop 0
	global_load_dwordx4 v[128:131], v[132:133], off offset:528 nt
	s_nop 0
	global_load_dwordx4 v[132:135], v[132:133], off offset:512 nt
	s_waitcnt vmcnt(0)
	v_pk_fma_f32 v[216:217], v[126:127], 0.5, v[216:217] op_sel_hi:[1,0,1]
	v_pk_fma_f32 v[214:215], v[124:125], 0.5, v[214:215] op_sel_hi:[1,0,1]
	v_pk_fma_f32 v[228:229], v[120:121], 0.5, v[210:211] op_sel_hi:[1,0,1]
	v_mul_f32_e32 v209, v215, v215
	v_mul_f32_e32 v210, v217, v217
	v_pk_fma_f32 v[230:231], v[122:123], 0.5, v[212:213] op_sel_hi:[1,0,1]
	v_fmac_f32_e32 v209, v214, v214
	v_fmac_f32_e32 v210, v216, v216
	v_add_f32_e32 v209, v209, v210
	v_mul_f32_e32 v210, v229, v229
	v_mul_f32_e32 v211, v231, v231
	v_fmac_f32_e32 v210, v228, v228
	v_fmac_f32_e32 v211, v230, v230
	v_add_f32_e32 v210, v210, v211
	v_pk_fma_f32 v[226:227], v[94:95], 0.5, v[226:227] op_sel_hi:[1,0,1]
	v_pk_fma_f32 v[224:225], v[92:93], 0.5, v[224:225] op_sel_hi:[1,0,1]
	v_add_f32_e32 v209, v209, v210
	v_mul_f32_e32 v210, v225, v225
	v_mul_f32_e32 v211, v227, v227
	v_pk_fma_f32 v[220:221], v[90:91], 0.5, v[220:221] op_sel_hi:[1,0,1]
	v_pk_fma_f32 v[218:219], v[88:89], 0.5, v[218:219] op_sel_hi:[1,0,1]
	v_fmac_f32_e32 v210, v224, v224
	v_fmac_f32_e32 v211, v226, v226
	v_add_f32_e32 v210, v210, v211
	v_mul_f32_e32 v211, v219, v219
	v_mul_f32_e32 v212, v221, v221
	v_fmac_f32_e32 v211, v218, v218
	v_fmac_f32_e32 v212, v220, v220
	v_add_f32_e32 v211, v211, v212
	v_add_f32_e32 v210, v210, v211
	v_add_f32_e32 v212, v209, v210
	v_and_b32_e32 v210, 64, v208
	v_xor_b32_e32 v209, 16, v208
	v_add_u32_e32 v213, 64, v210
	v_cmp_lt_i32_e32 vcc, v209, v213
	v_lshl_add_u64 v[210:211], s[12:13], 0, v[234:235]
	v_lshl_add_u64 v[232:233], v[210:211], 0, v[232:233]
	v_cndmask_b32_e32 v209, v208, v209, vcc
	v_lshlrev_b32_e32 v209, 2, v209
	ds_bpermute_b32 v223, v209, v212
	v_xor_b32_e32 v210, 32, v208
	v_cmp_lt_i32_e32 vcc, v210, v213
	global_store_dwordx4 v[232:233], v[214:217], off
	global_store_dwordx4 v[232:233], v[228:231], off offset:16
	global_store_dwordx4 v[232:233], v[224:227], off offset:512
	global_store_dwordx4 v[232:233], v[218:221], off offset:528
	v_cndmask_b32_e32 v210, v208, v210, vcc
	s_waitcnt lgkmcnt(0)
	v_add_f32_e32 v211, v212, v223
	v_lshlrev_b32_e32 v210, 2, v210
	ds_bpermute_b32 v212, v210, v211
	s_and_saveexec_b64 s[48:49], s[4:5]
	s_cbranch_execz .LBB0_1295
	s_waitcnt lgkmcnt(0)
	v_add_f32_e32 v211, v211, v212
	v_lshl_add_u64 v[212:213], v[192:193], 2, s[40:41]
	global_atomic_add_f32 v[212:213], v211, off

; __device__ __forceinline__ unsigned pk2(float lo, float hi) { unsigned r; asm volatile("v_cvt_pk_bf16_f32 %0, %1, %2" : "=v"(r) : "v"(lo), "v"(hi)); return r; }
; __device__ __forceinline__ float dot4(f32x4 v) { return (v[0] * v[0] + v[1] * v[1]) + (v[2] * v[2] + v[3] * v[3]); }
;     __device__ __forceinline__ void operator()(const f32x4 (&acc)[2][2][4][2], const Unit& u, int wr, int wc, int fr, int fq) const {
;     ...
;             for (int m = 0; m < 4; ++m)
; #pragma unroll
;                 for (int bj = 0; bj < 2; ++bj) { const size_t off = (size_t)(row0 + ai * HALF + m * 16) * D + col0 + bj * HALF;
;                     if (quad >= 0 && (quad & 1) != bj) { rr[m][bj][0] = (f32x4){0.f, 0.f, 0.f, 0.f}; rr[m][bj][1] = rr[m][bj][0]; }
;                     else { rr[m][bj][0] = *(const f32x4*)(bb + off); rr[m][bj][1] = *(const f32x4*)(bb + off + 4); } }
;             __builtin_amdgcn_sched_barrier(0);
; #pragma unroll
;             for (int m = 0; m < 4; ++m) {
;                 const int row = row0 + ai * HALF + m * 16; const size_t off = (size_t)row * D + col0;
;                 float q = 0.f;
; #pragma unroll
;                 for (int bj = 0; bj < 2; ++bj) {
;                     if (quad >= 0 && (quad & 1) != bj) continue;
;                     const f32x4 v0 = rr[m][bj][0] + acc[ai][bj][m][0] * scale, v1 = rr[m][bj][1] + acc[ai][bj][m][1] * scale;
;                     q += dot4(v0) + dot4(v1);
;                     __builtin_nontemporal_store(v0, (f32x4*)(out + off + bj * HALF)); __builtin_nontemporal_store(v1, (f32x4*)(out + off + bj * HALF + 4));
;                     if (An) { const f32x4 a0 = v0 * gv[bj][0], a1 = v1 * gv[bj][1]; u32x4 w; w.x = pk2(a0[0], a0[1]); w.y = pk2(a0[2], a0[3]); w.z = pk2(a1[0], a1[1]); w.w = pk2(a1[2], a1[3]);
;                         *(u32x4*)(An + off + bj * HALF) = w; }
;                 }
;                 q += __shfl_xor(q, 16); q += __shfl_xor(q, 32);
;                 if (fq == 0) __hip_atomic_fetch_add(ss + row, q, __ATOMIC_RELAXED, __HIP_MEMORY_SCOPE_AGENT);
.LBB0_1301:
	s_or_b64 exec, exec, s[48:49]
	v_add_u32_e32 v204, 0x80, v192
	v_ashrrev_i32_e32 v205, 31, v204
	v_add_u32_e32 v200, 0x90, v192
	v_lshlrev_b64 v[220:221], 13, v[204:205]
	v_ashrrev_i32_e32 v201, 31, v200
	v_add_u32_e32 v196, 0xa0, v192
	v_add_u32_e32 v192, 0xb0, v192
	s_waitcnt lgkmcnt(0)
	v_lshl_add_u64 v[128:129], v[190:191], 0, v[220:221]
	v_lshlrev_b64 v[202:203], 13, v[200:201]
	v_ashrrev_i32_e32 v197, 31, v196
	v_ashrrev_i32_e32 v193, 31, v192
	global_load_dwordx4 v[212:215], v[128:129], off offset:16 nt
	global_load_dwordx4 v[216:219], v[128:129], off nt
	global_load_dwordx4 v[224:227], v[128:129], off offset:528 nt
	global_load_dwordx4 v[228:231], v[128:129], off offset:512 nt
	v_lshl_add_u64 v[128:129], v[190:191], 0, v[202:203]
	v_lshlrev_b64 v[198:199], 13, v[196:197]
	v_lshlrev_b64 v[194:195], 13, v[192:193]
	global_load_dwordx4 v[168:171], v[128:129], off offset:16 nt
	global_load_dwordx4 v[172:175], v[128:129], off nt
	global_load_dwordx4 v[160:163], v[128:129], off offset:528 nt
	global_load_dwordx4 v[164:167], v[128:129], off offset:512 nt
	v_lshl_add_u64 v[128:129], v[190:191], 0, v[198:199]
	v_lshl_add_u64 v[132:133], v[190:191], 0, v[194:195]
	global_load_dwordx4 v[152:155], v[128:129], off offset:16 nt
	global_load_dwordx4 v[156:159], v[128:129], off nt
	global_load_dwordx4 v[144:147], v[128:129], off offset:528 nt
	global_load_dwordx4 v[148:151], v[128:129], off offset:512 nt
	global_load_dwordx4 v[136:139], v[132:133], off offset:16 nt
	global_load_dwordx4 v[140:143], v[132:133], off nt
	s_nop 0
	global_load_dwordx4 v[128:131], v[132:133], off offset:528 nt
	s_nop 0
	global_load_dwordx4 v[132:135], v[132:133], off offset:512 nt
	s_waitcnt vmcnt(14)
	v_pk_fma_f32 v[218:219], v[62:63], 0.5, v[218:219] op_sel_hi:[1,0,1]
	v_pk_fma_f32 v[216:217], v[60:61], 0.5, v[216:217] op_sel_hi:[1,0,1]
	v_mul_f32_e32 v191, v219, v219
	v_mul_f32_e32 v190, v217, v217
	v_pk_fma_f32 v[214:215], v[58:59], 0.5, v[214:215] op_sel_hi:[1,0,1]
	v_pk_fma_f32 v[212:213], v[56:57], 0.5, v[212:213] op_sel_hi:[1,0,1]
	v_fmac_f32_e32 v190, v216, v216
	v_fmac_f32_e32 v191, v218, v218
	v_add_f32_e32 v190, v190, v191
	v_mul_f32_e32 v191, v213, v213
	v_mul_f32_e32 v211, v215, v215
	v_fmac_f32_e32 v191, v212, v212
	v_fmac_f32_e32 v211, v214, v214
	v_add_f32_e32 v191, v191, v211
	s_waitcnt vmcnt(12)
	v_pk_fma_f32 v[230:231], v[30:31], 0.5, v[230:231] op_sel_hi:[1,0,1]
	v_pk_fma_f32 v[228:229], v[28:29], 0.5, v[228:229] op_sel_hi:[1,0,1]
	v_add_f32_e32 v190, v190, v191
	v_mul_f32_e32 v191, v229, v229
	v_mul_f32_e32 v211, v231, v231
	v_pk_fma_f32 v[226:227], v[26:27], 0.5, v[226:227] op_sel_hi:[1,0,1]
	v_pk_fma_f32 v[224:225], v[24:25], 0.5, v[224:225] op_sel_hi:[1,0,1]
	v_fmac_f32_e32 v191, v228, v228
	v_fmac_f32_e32 v211, v230, v230
	v_add_f32_e32 v191, v191, v211
	v_mul_f32_e32 v211, v225, v225
	v_mul_f32_e32 v223, v227, v227
	v_fmac_f32_e32 v211, v224, v224
	v_fmac_f32_e32 v223, v226, v226
	v_add_f32_e32 v211, v211, v223
	v_add_f32_e32 v191, v191, v211
	v_add_f32_e32 v211, v190, v191
	ds_bpermute_b32 v223, v209, v211
	v_lshl_add_u64 v[190:191], s[12:13], 0, v[220:221]
	v_lshl_add_u64 v[220:221], v[188:189], 2, v[190:191]
	global_store_dwordx4 v[220:221], v[216:219], off
	global_store_dwordx4 v[220:221], v[212:215], off offset:16
	global_store_dwordx4 v[220:221], v[228:231], off offset:512
	global_store_dwordx4 v[220:221], v[224:227], off offset:528
	s_waitcnt lgkmcnt(0)
	v_add_f32_e32 v190, v211, v223
	ds_bpermute_b32 v191, v210, v190
	s_and_saveexec_b64 s[48:49], s[4:5]
	s_cbranch_execz .LBB0_1303
	s_waitcnt lgkmcnt(0)
	v_add_f32_e32 v211, v190, v191
	v_lshl_add_u64 v[190:191], v[204:205], 2, s[40:41]
	global_atomic_add_f32 v[190:191], v211, off
